# stack + hyena ctx item prologue: 3 conv3 with all loads in flight, compute deferred behind one wait
# speedup vs baseline: 1.0159x; 1.0022x over previous
.LBB0_931:
	s_or_b64 exec, exec, s[0:1]
	s_waitcnt lgkmcnt(0)
	s_barrier
	ds_read_b32 v0, v1 offset:16
	s_movk_i32 s0, 0x80f
	s_waitcnt lgkmcnt(0)
	v_cmp_lt_i32_e32 vcc, s0, v0
	v_readfirstlane_b32 s50, v0
	s_mov_b64 s[0:1], -1
	s_cbranch_vccnz .LBB0_926
	s_add_i32 s36, s50, 0xfffffe00
	s_mov_b32 s45, s51
	s_cmpk_gt_u32 s36, 0x40f
	s_cbranch_scc0 .LBB0_972
	s_cmpk_gt_i32 s50, 0x1ff
	s_mov_b32 s6, 0x8200
	s_movk_i32 s20, 0xfd
	s_mov_b32 s26, 0x41800000
	s_cbranch_scc0 .LBB0_973
	s_mov_b64 s[22:23], 0
	s_cmpk_gt_u32 s50, 0x60f
	s_mov_b64 s[0:1], 0
	s_cbranch_scc0 .LBB0_974
	s_waitcnt vmcnt(5)
	v_mov_b32_e32 v18, v179
	v_readlane_b32 s0, v254, 57
	v_lshrrev_b32_e32 v0, 8, v18
	s_mov_b32 s5, s45
	s_add_i32 s4, s50, 0xfffff9f0
	v_mul_hi_i32_i24_e32 v3, 0x600, v0
	v_mul_i32_i24_e32 v2, 0x600, v0
	v_readlane_b32 s1, v254, 58
	v_lshl_add_u64 v[4:5], v[2:3], 0, s[4:5]
	s_mov_b64 s[44:45], s[4:5]
	v_mov_b64_e32 v[2:3], s[0:1]
	v_mad_u64_u32 v[2:3], s[0:1], v4, s6, v[2:3]
	v_mov_b32_e32 v0, v3
	v_mad_u64_u32 v[4:5], s[0:1], v5, s6, v[0:1]
	s_lshl_b64 s[24:25], s[4:5], 2
	v_readlane_b32 s0, v254, 23
	v_readlane_b32 s2, v254, 25
	v_readlane_b32 s3, v254, 26
	s_add_u32 s2, s2, s24
	v_readlane_b32 s4, v254, 27
	v_readlane_b32 s8, v254, 31
	s_addc_u32 s3, s3, s25
	s_waitcnt vmcnt(4)
	v_and_b32_e32 v17, 0xff, v18
	v_readlane_b32 s5, v254, 28
	v_readlane_b32 s9, v254, 32
	s_add_u32 s8, s4, s24
	v_mov_b32_e32 v3, v4
	s_addc_u32 s9, s5, s25
	v_lshlrev_b32_e32 v0, 1, v17
	v_lshl_add_u64 v[10:11], v[2:3], 0, v[0:1]
	v_mov_b32_e32 v33, 0
	v_mov_b32_e32 v34, 0
	v_mov_b32_e32 v35, 0
	v_mov_b32_e32 v36, 0
	v_mov_b32_e32 v37, 0
	v_mov_b32_e32 v38, 0
	v_mov_b32_e32 v39, 0
	v_mov_b32_e32 v40, 0
	v_mov_b32_e32 v41, 0
	v_mov_b32_e32 v42, 0
	v_mov_b32_e32 v43, 0
	v_mov_b32_e32 v44, 0
	v_mov_b32_e32 v45, 0
	v_mov_b32_e32 v46, 0
	v_mov_b32_e32 v47, 0
	v_mov_b32_e32 v48, 0
	v_mov_b32_e32 v49, 0
	v_mov_b32_e32 v50, 0
	global_load_dword v15, v1, s[8:9]
	global_load_ushort v33, v[10:11], off
	global_load_dword v34, v235, s[2:3] offset:2048
	global_load_dword v35, v196, s[2:3]
	v_readlane_b32 s6, v254, 29
	v_readlane_b32 s7, v254, 30
	v_readlane_b32 s1, v254, 24
	v_cmp_eq_u32_e64 s[4:5], 0, v17
	v_cmp_ne_u32_e64 s[6:7], 0, v17
	v_readlane_b32 s10, v254, 33
	v_readlane_b32 s11, v254, 34
	v_readlane_b32 s12, v254, 35
	v_readlane_b32 s13, v254, 36
	v_readlane_b32 s14, v254, 37
	v_readlane_b32 s15, v254, 38
	s_and_saveexec_b64 s[0:1], s[6:7]
	s_cbranch_execz .LBB0_937
	global_load_ushort v36, v[10:11], off offset:-2
	global_load_dword v37, v1, s[2:3]
.LBB0_937:
	s_or_b64 exec, exec, s[0:1]
	s_movk_i32 s0, 0xff
	v_cmp_ne_u32_e64 s[0:1], s0, v17
	s_and_saveexec_b64 s[16:17], s[0:1]
	s_cbranch_execz .LBB0_939
	global_load_ushort v38, v[10:11], off offset:2
.LBB0_939:
	s_or_b64 exec, exec, s[16:17]
	v_lshl_add_u64 v[4:5], v[2:3], 0, v[0:1]
	v_add_co_u32_e32 v6, vcc, 0x1040000, v4
	global_load_dword v16, v1, s[8:9] offset:2048
	s_nop 0
	v_addc_co_u32_e32 v7, vcc, 0, v5, vcc
	global_load_ushort v39, v[6:7], off
	v_mov_b32_e32 v6, 0x2000
	global_load_dword v40, v6, s[2:3]
	s_nop 0
	global_load_dword v41, v196, s[2:3] offset:2048
	s_mov_b64 s[14:15], 0x1040000
	v_lshl_add_u64 v[4:5], v[4:5], 0, s[14:15]
	s_and_saveexec_b64 s[14:15], s[6:7]
	s_cbranch_execz .LBB0_941
	global_load_ushort v42, v[4:5], off offset:-2
	global_load_dword v43, v1, s[2:3] offset:2048
.LBB0_941:
	s_or_b64 exec, exec, s[14:15]
	s_and_saveexec_b64 s[14:15], s[0:1]
	s_cbranch_execz .LBB0_943
	global_load_ushort v44, v[4:5], off offset:2
.LBB0_943:
	s_or_b64 exec, exec, s[14:15]
	s_mov_b64 s[14:15], s[44:45]
	s_bitset1_b32 s14, 10
	v_readlane_b32 s64, v254, 23
	s_lshl_b64 s[12:13], s[14:15], 2
	v_readlane_b32 s68, v254, 27
	v_readlane_b32 s69, v254, 28
	s_add_u32 s14, s68, s12
	s_addc_u32 s15, s69, s13
	global_load_dword v14, v1, s[14:15]
	v_lshl_add_u64 v[6:7], v[2:3], 0, v[0:1]
	s_mov_b64 s[14:15], 0x2080000
	v_lshl_add_u64 v[2:3], v[6:7], 0, s[14:15]
	v_add_co_u32_e32 v6, vcc, 0x2080000, v6
	v_mov_b32_e32 v4, 0x2000
	s_nop 0
	v_addc_co_u32_e32 v7, vcc, 0, v7, vcc
	global_load_ushort v45, v[6:7], off
	global_load_dword v46, v4, s[2:3] offset:2048
	v_mov_b32_e32 v4, 0x4000
	global_load_dword v47, v4, s[2:3]
	v_readlane_b32 s65, v254, 24
	v_readlane_b32 s66, v254, 25
	v_readlane_b32 s67, v254, 26
	v_readlane_b32 s70, v254, 29
	v_readlane_b32 s71, v254, 30
	v_readlane_b32 s72, v254, 31
	v_readlane_b32 s73, v254, 32
	v_readlane_b32 s74, v254, 33
	v_readlane_b32 s75, v254, 34
	v_readlane_b32 s76, v254, 35
	v_readlane_b32 s77, v254, 36
	v_readlane_b32 s78, v254, 37
	v_readlane_b32 s79, v254, 38
	s_and_saveexec_b64 s[14:15], s[6:7]
	s_cbranch_execz .LBB0_945
	v_readlane_b32 s64, v254, 23
	v_readlane_b32 s66, v254, 25
	v_readlane_b32 s67, v254, 26
	s_add_u32 s6, s66, s12
	s_addc_u32 s7, s67, s13
	global_load_ushort v48, v[2:3], off offset:-2
	global_load_dword v49, v1, s[6:7]
	v_readlane_b32 s65, v254, 24
	v_readlane_b32 s68, v254, 27
	v_readlane_b32 s69, v254, 28
	v_readlane_b32 s70, v254, 29
	v_readlane_b32 s71, v254, 30
	v_readlane_b32 s72, v254, 31
	v_readlane_b32 s73, v254, 32
	v_readlane_b32 s74, v254, 33
	v_readlane_b32 s75, v254, 34
	v_readlane_b32 s76, v254, 35
	v_readlane_b32 s77, v254, 36
	v_readlane_b32 s78, v254, 37
	v_readlane_b32 s79, v254, 38
.LBB0_945:
	s_or_b64 exec, exec, s[14:15]
	s_and_saveexec_b64 s[6:7], s[0:1]
	s_cbranch_execz .LBB0_947
	global_load_ushort v50, v[2:3], off offset:2
.LBB0_947:
	s_or_b64 exec, exec, s[6:7]
	s_waitcnt vmcnt(0)
	v_lshlrev_b32_e32 v33, 16, v33
	v_fmac_f32_e32 v15, v34, v33
	v_lshlrev_b32_e32 v36, 16, v36
	v_fmac_f32_e32 v15, v37, v36
	v_lshlrev_b32_e32 v38, 16, v38
	v_fmac_f32_e32 v15, v35, v38
	v_lshlrev_b32_e32 v39, 16, v39
	v_fmac_f32_e32 v16, v40, v39
	v_lshlrev_b32_e32 v42, 16, v42
	v_fmac_f32_e32 v16, v43, v42
	v_lshlrev_b32_e32 v44, 16, v44
	v_fmac_f32_e32 v16, v41, v44
	v_lshlrev_b32_e32 v45, 16, v45
	v_fmac_f32_e32 v14, v46, v45
	v_lshlrev_b32_e32 v48, 16, v48
	v_fmac_f32_e32 v14, v49, v48
	v_lshlrev_b32_e32 v50, 16, v50
	v_fmac_f32_e32 v14, v47, v50
	s_movk_i32 s6, 0xff
	s_lshl_b32 s9, s44, 8
	v_cmp_lt_u32_e64 s[6:7], s6, v18
	v_lshl_add_u32 v20, v17, 2, 32
	v_or_b32_e32 v12, s9, v17
	s_barrier
	s_and_saveexec_b64 s[12:13], s[6:7]
	s_xor_b64 s[12:13], exec, s[12:13]
	s_cbranch_execz .LBB0_949
	v_readlane_b32 s14, v251, 54
	v_mov_b32_e32 v13, v1
	v_readlane_b32 s15, v251, 55
	s_nop 1
	v_lshl_add_u64 v[2:3], v[12:13], 2, s[14:15]
	v_add_co_u32_e32 v2, vcc, 0x100000, v2
	s_nop 1
	v_addc_co_u32_e32 v3, vcc, 0, v3, vcc
	global_load_dword v0, v[2:3], off
	s_waitcnt vmcnt(0)
	ds_write_b32 v20, v0 offset:3072
	v_cndmask_b32_e64 v2, v0, 0, s[4:5]
